# stick-breaking key-tile steps: bpermute lane-index registers computed once per phase instead of in every step
# speedup vs baseline: 1.0031x; 1.0031x over previous
; #define LAS __attribute__((address_space(3)))
; __device__ __forceinline__ void sb_unit(LAS unsigned char* lds, const bf16_t* P0, bf16_t* MIX, int b, int h, int qc) {
;     const int tid = threadIdx.x, lane = tid & 63, w = tid >> 6, fr = lane & 15, fq = lane >> 4;
;     LAS bf16_t* Ks = (LAS bf16_t*)lds;
;     LAS bf16_t* Vl = Ks + 128 * 72;
;     const size_t rowbase = (size_t)b * SEQ; const int q0 = qc * 128, tq = q0 + 16 * w + fr;
;     const bf16_t* qp = P0 + (rowbase + tq) * AB_IN + 1024 + 64 * h + 8 * fq;
;     const bf16x8 qf0 = *(const bf16x8*)qp, qf1 = *(const bf16x8*)(qp + 32);
;     f32x4 oacc[4];
; #pragma unroll
;     for (int n = 0; n < 4; ++n) oacc[n] = (f32x4){0.f, 0.f, 0.f, 0.f};
;     float R = 1.f;
;     LAS unsigned* flags = (LAS unsigned*)(Vl + 128 * 72);
;     u32x4 pkr[2], pvr[2];
;     const int krow = tid >> 3, kc8 = tid & 7, vs_ = tid & 127, vc8 = tid >> 7;
;     ...
;             const float t1 = __shfl_xor(x0, 16), t2 = __shfl_xor(x0, 32), t3 = __shfl_xor(t1, 32);
.LBB0_285:
	s_cmp_lt_i32 s72, 3
	s_cselect_b64 s[0:1], -1, 0
	s_add_u32 s40, s50, 0xa200000
	s_addc_u32 s41, s51, 0
	s_and_b64 s[4:5], s[0:1], s[4:5]
	s_andn2_b64 vcc, exec, s[4:5]
	s_cbranch_vccnz .LBB0_382
	s_cmpk_gt_i32 s2, 0xbff
	s_cbranch_scc1 .LBB0_382
	v_and_b32_e32 v240, 63, v176
	v_xor_b32_e32 v241, 32, v240
	v_xor_b32_e32 v240, 16, v240
	v_lshlrev_b32_e32 v240, 2, v240
	v_lshlrev_b32_e32 v241, 2, v241
	v_lshlrev_b32_e32 v0, 5, v176
	v_writelane_b32 v254, s4, 20
	v_lshrrev_b32_e32 v81, 2, v176
	v_and_b32_e32 v0, 0x60, v0
	v_writelane_b32 v254, s5, 21
	v_cmp_gt_u32_e64 s[4:5], v0, v81
	v_or_b32_e32 v2, 2, v0
	v_lshl_add_u32 v3, v0, 1, 0
	v_writelane_b32 v254, s4, 18
	s_movk_i32 s0, 0x110
	v_mad_u32_u24 v85, v81, s0, v3
	v_writelane_b32 v254, s5, 19
	v_cmp_lt_u32_e64 s[4:5], v0, v81
	v_mov_b32_e32 v73, 0
	v_lshlrev_b32_e32 v72, 2, v0
	v_writelane_b32 v254, s4, 16
	v_lshl_add_u64 v[74:75], s[28:29], 0, v[72:73]
	v_lshl_add_u64 v[76:77], s[30:31], 0, v[72:73]
	v_writelane_b32 v254, s5, 17
	v_cmp_gt_u32_e64 s[4:5], v2, v81
	v_or_b32_e32 v2, 3, v0
	v_and_b32_e32 v1, 15, v176
	v_writelane_b32 v254, s4, 14
	v_bfe_u32 v5, v176, 4, 2
	v_bfe_u32 v8, v176, 2, 2
	v_writelane_b32 v254, s5, 15
	v_cmp_gt_u32_e64 s[4:5], v2, v81
	v_or_b32_e32 v2, 4, v0
	v_lshlrev_b32_e32 v80, 2, v5
	v_writelane_b32 v254, s4, 10
	v_lshl_or_b32 v89, v224, 4, v1
	v_and_b32_e32 v14, 48, v176
	v_writelane_b32 v254, s5, 11
	v_cmp_gt_u32_e64 s[4:5], v2, v81
	v_or_b32_e32 v2, 5, v0
	v_and_b32_e32 v84, 0x7f, v176
	v_writelane_b32 v254, s4, 12
	v_lshrrev_b32_e32 v6, 7, v176
	v_lshlrev_b32_e32 v88, 3, v6
	v_writelane_b32 v254, s5, 13
	v_cmp_gt_u32_e64 s[4:5], v2, v81
	v_or_b32_e32 v2, 6, v0
	v_lshlrev_b32_e32 v13, 4, v6
	v_writelane_b32 v254, s4, 22
	v_add_u32_e32 v103, 1, v6
	v_lshlrev_b32_e32 v6, 4, v5
	v_writelane_b32 v254, s5, 23
	v_cmp_gt_u32_e64 s[4:5], v2, v81
	v_or_b32_e32 v2, 7, v0
	v_mbcnt_lo_u32_b32 v111, -1, 0
	v_writelane_b32 v254, s4, 24
	v_lshrrev_b32_e32 v82, 3, v176
	v_and_b32_e32 v11, 7, v176
	v_writelane_b32 v254, s5, 25
	v_cmp_gt_u32_e64 s[4:5], v2, v81
	v_or_b32_e32 v2, 8, v0
	v_cmp_gt_u32_e64 s[0:1], v2, v81
	v_writelane_b32 v254, s4, 26
	v_mbcnt_hi_u32_b32 v112, -1, v111
	v_mul_u32_u24_e32 v4, 0x110, v81
	v_writelane_b32 v254, s5, 27
	v_writelane_b32 v254, s0, 28
	v_and_b32_e32 v10, 63, v176
	v_lshlrev_b32_e32 v86, 3, v11
	v_writelane_b32 v254, s1, 29
	v_cmp_lt_u32_e64 s[0:1], v2, v81
	v_or_b32_e32 v2, 10, v0
	v_lshl_add_u32 v11, v11, 4, 0
	v_writelane_b32 v254, s0, 30
	v_cmp_ne_u32_e64 s[72:73], 1, v5
	v_cmp_eq_u32_e64 s[74:75], 2, v5
	v_writelane_b32 v254, s1, 31
	v_cmp_gt_u32_e64 s[0:1], v2, v81
	v_or_b32_e32 v2, 11, v0
	v_lshlrev_b32_e32 v90, 1, v0
	v_writelane_b32 v254, s0, 32
	s_mov_b32 s23, 0
	v_lshlrev_b32_e32 v83, 7, v81
	v_writelane_b32 v254, s1, 33
	v_cmp_gt_u32_e64 s[0:1], v2, v81
	v_or_b32_e32 v2, 12, v0
	v_lshl_add_u64 v[78:79], s[52:53], 0, v[72:73]
	v_writelane_b32 v254, s0, 34
	v_cmp_lt_u32_e64 s[70:71], 15, v10
	v_cmp_eq_u32_e64 s[76:77], 0, v10
	v_writelane_b32 v254, s1, 35
	v_cmp_gt_u32_e64 s[0:1], v2, v81
	v_or_b32_e32 v2, 13, v0
	v_lshl_add_u32 v102, v224, 2, 0
	v_writelane_b32 v254, s0, 36
	v_cmp_gt_u32_e64 s[90:91], 64, v176
	s_movk_i32 s3, 0x1400
	v_writelane_b32 v254, s1, 37
	v_cmp_gt_u32_e64 s[0:1], v2, v81
	v_or_b32_e32 v2, 14, v0
	v_mov_b32_e32 v106, 0x3727c5ac
	v_writelane_b32 v254, s0, 38
	v_add_u32_e32 v107, v3, v4
	v_lshlrev_b32_e32 v92, 1, v80
	v_writelane_b32 v254, s1, 39
	v_cmp_gt_u32_e64 s[0:1], v2, v81
	v_or_b32_e32 v2, 15, v0
	s_mov_b64 s[18:19], 0x1000
	v_writelane_b32 v254, s0, 40
	v_xor_b32_e32 v113, 1, v112
	v_xor_b32_e32 v115, 2, v112
	v_writelane_b32 v254, s1, 41
	v_cmp_gt_u32_e64 s[0:1], v2, v81
	v_or_b32_e32 v2, 16, v0
	s_mov_b32 s33, s2
	v_writelane_b32 v254, s0, 42
	s_nop 1
	v_writelane_b32 v254, s1, 43
	v_cmp_gt_u32_e64 s[0:1], v2, v81
	s_nop 1
	v_writelane_b32 v254, s0, 44
	s_nop 1
	v_writelane_b32 v254, s1, 45
	v_cmp_lt_u32_e64 s[0:1], v2, v81
	v_or_b32_e32 v2, 18, v0
	s_nop 0
	v_writelane_b32 v254, s0, 46
	s_nop 1
	v_writelane_b32 v254, s1, 47
	v_cmp_gt_u32_e64 s[0:1], v2, v81
	v_or_b32_e32 v2, 19, v0
	s_nop 0
	v_writelane_b32 v254, s0, 48
	s_nop 1
	v_writelane_b32 v254, s1, 49
	v_cmp_gt_u32_e64 s[0:1], v2, v81
	v_or_b32_e32 v2, 20, v0
	s_nop 0
	v_writelane_b32 v254, s0, 50
	s_nop 1
	v_writelane_b32 v254, s1, 51
	v_cmp_gt_u32_e64 s[0:1], v2, v81
	v_or_b32_e32 v2, 21, v0
	s_nop 0
	v_writelane_b32 v254, s0, 52
	s_nop 1
	v_writelane_b32 v254, s1, 53
	v_cmp_gt_u32_e64 s[0:1], v2, v81
	v_or_b32_e32 v2, 22, v0
	s_nop 0
	v_writelane_b32 v254, s0, 54
	s_nop 1
	v_writelane_b32 v254, s1, 55
	v_cmp_gt_u32_e64 s[0:1], v2, v81
	v_or_b32_e32 v2, 23, v0
	s_nop 0
	v_writelane_b32 v254, s0, 56
	s_nop 1
	v_writelane_b32 v254, s1, 57
	v_cmp_gt_u32_e64 s[0:1], v2, v81
	v_or_b32_e32 v2, 24, v0
	s_nop 0
	v_writelane_b32 v254, s0, 58
	s_nop 1
	v_writelane_b32 v254, s1, 59
	v_cmp_gt_u32_e64 s[0:1], v2, v81
	s_nop 1
	v_writelane_b32 v254, s0, 60
	s_nop 1
	v_writelane_b32 v254, s1, 61
	v_cmp_lt_u32_e64 s[0:1], v2, v81
	v_or_b32_e32 v2, 26, v0
	v_cmp_gt_u32_e64 s[64:65], v2, v81
	v_or_b32_e32 v2, 27, v0
	v_cmp_gt_u32_e64 s[28:29], v2, v81
	v_or_b32_e32 v2, 28, v0
	v_cmp_gt_u32_e64 s[30:31], v2, v81
	v_or_b32_e32 v2, 29, v0
	v_cmp_gt_u32_e64 s[34:35], v2, v81
	v_or_b32_e32 v2, 30, v0
	v_writelane_b32 v254, s0, 62
	v_cmp_gt_u32_e64 s[38:39], v2, v81
	v_or_b32_e32 v2, 31, v0
	v_writelane_b32 v254, s1, 63
	v_cmp_gt_u32_e64 s[68:69], v2, v81
	s_movk_i32 s0, 0xf0
	v_lshlrev_b32_e32 v2, 3, v176
	v_and_or_b32 v87, v81, s0, v1
	v_and_b32_e32 v2, 24, v2
	v_mul_u32_u24_e32 v1, 0x90, v1
	v_add_u32_e32 v9, 0, v2
	s_movk_i32 s0, 0x90
	v_add3_u32 v100, 0, v1, v14
	v_or_b32_e32 v1, v80, v8
	v_mad_u32_u24 v12, v84, s0, 0
	v_mad_u32_u24 v101, v1, s0, v9
	s_movk_i32 s0, 0x1c0
	v_cmp_gt_u32_e64 s[78:79], s0, v176
	s_movk_i32 s0, 0x180
	v_cmp_gt_u32_e64 s[80:81], s0, v176
	s_movk_i32 s0, 0x140
	v_cmp_gt_u32_e64 s[82:83], s0, v176
	s_movk_i32 s0, 0x100
	v_cmp_gt_u32_e64 s[84:85], s0, v176
	s_movk_i32 s0, 0xc0
	v_cmp_gt_u32_e64 s[86:87], s0, v176
	s_movk_i32 s0, 0x80
	v_mul_u32_u24_e32 v7, 0x110, v87
	v_cmp_gt_u32_e64 s[88:89], s0, v176
	s_mov_b32 s0, 0x8800
	v_add3_u32 v104, v7, v6, s0
	v_and_b32_e32 v7, 3, v176
	v_lshlrev_b32_e32 v2, 3, v5
	v_mul_u32_u24_e32 v14, 0x90, v1
	v_mul_u32_u24_e32 v1, 0x90, v82
	v_mul_u32_u24_e32 v5, 0x880, v5
	v_mul_u32_u24_e32 v6, 0x110, v8
	v_lshlrev_b32_e32 v7, 3, v7
	v_and_b32_e32 v0, 64, v112
	v_add3_u32 v105, v5, v6, v7
	v_lshlrev_b32_e32 v94, 1, v2
	v_add_u32_e32 v108, v11, v1
	v_add_u32_e32 v109, v12, v13
	v_add_u32_e32 v110, v9, v14
	v_add_u32_e32 v114, 64, v0
	s_branch .LBB0_290

; __device__ __forceinline__ u32x2 pack4(f32x4 v) { return (u32x2){pk2(v[0], v[1]), pk2(v[2], v[3])}; }
; #define SB0 __builtin_amdgcn_sched_barrier(0)
; #define SK_LOAD(m_) do { kfr[(m_) & 1][0] = *(const LAS bf16x8*)(Ks + (16 * (m_) + fr) * 72 + 8 * fq); kfr[(m_) & 1][1] = *(const LAS bf16x8*)(Ks + (16 * (m_) + fr) * 72 + 32 + 8 * fq); } while (0)
; #define SB0 __builtin_amdgcn_sched_barrier(0)
; __device__ __forceinline__ void sb_unit(LAS unsigned char* lds, const bf16_t* P0, bf16_t* MIX, int b, int h, int qc) {
;     ...
;         for (int m = 7; m >= 0; --m) {
;             if (m > 0) SK_LOAD(m - 1);
;             SB0;
;             if (diag && m > w) { pk[m] = (u32x2){0u, 0u}; continue; }
;             f32x4 z = (f32x4){0.f, 0.f, 0.f, 0.f};
;             z = __builtin_amdgcn_mfma_f32_16x16x32_bf16(kfr[m & 1][0], qf0, z, 0, 0, 0);
;             z = __builtin_amdgcn_mfma_f32_16x16x32_bf16(kfr[m & 1][1], qf1, z, 0, 0, 0);
;             const int sb = kb * 128 + 16 * m + 4 * fq;
;             float be[4], om[4];
; #pragma unroll
;             for (int r = 0; r < 4; ++r) { const bool ok = !diag || (sb + r < tq);
;                 const float e = __builtin_amdgcn_exp2f(-fabsf(z[r])), inv = __builtin_amdgcn_rcpf(1.f + e), ei = e * inv;
;                 be[r] = ok ? (z[r] >= 0.f ? inv : ei) : 0.f; om[r] = ok ? (z[r] >= 0.f ? ei : inv) : 1.f; }
;             const float x3 = om[3], x2 = x3 * om[2], x1 = x2 * om[1], x0 = x1 * om[0];
;             const float t1 = __shfl_xor(x0, 16), t2 = __shfl_xor(x0, 32), t3 = __shfl_xor(t1, 32);
;             const float E = fq == 0 ? (t1 * t2 * t3) : fq == 1 ? (t2 * t3) : fq == 2 ? t1 : 1.f;
;             const float base = R * E;
;             f32x4 av;
;             av[0] = be[0] * (x1 * base); av[1] = be[1] * (x2 * base); av[2] = be[2] * (x3 * base); av[3] = be[3] * base;
;             pk[m] = pack4(av);
;             R *= (x0 * t1) * (t2 * t3);
.LBB0_299:
	ds_read_b128 v[56:59], v100 offset:16128
	ds_read_b128 v[52:55], v100 offset:16192
	ds_read_b128 v[48:51], v100 offset:13824
	ds_read_b128 v[44:47], v100 offset:13888
	v_subrev_co_u32_e64 v99, s[4:5], 1, v95
	v_or_b32_e32 v116, s0, v80
	s_and_b64 s[0:1], s[78:79], s[4:5]
	s_xor_b64 s[0:1], s[0:1], -1
	v_mov_b32_e32 v43, 0
	v_mov_b32_e32 v42, 0
	s_and_saveexec_b64 s[6:7], s[0:1]
	s_cbranch_execz .LBB0_309
	s_waitcnt lgkmcnt(3)
	v_mfma_f32_16x16x32_bf16 v[40:43], v[56:59], v[0:3], 0
	v_or_b32_e32 v56, 0x70, v116
	v_cmp_ge_u32_e64 s[0:1], v56, v91
	s_and_b64 s[8:9], s[4:5], s[0:1]
	s_waitcnt lgkmcnt(2)
	v_mfma_f32_16x16x32_bf16 v[60:63], v[52:55], v[4:7], v[40:43]
	v_or_b32_e32 v52, 0x71, v116
	v_cmp_ge_u32_e64 s[96:97], v52, v91
	s_and_b64 s[42:43], s[4:5], s[96:97]
	s_nop 4
	v_exp_f32_e64 v40, -|v60|
	v_exp_f32_e64 v41, -|v61|
	v_exp_f32_e64 v52, -|v62|
	v_cmp_le_f32_e64 s[94:95], 0, v61
	v_add_f32_e32 v42, 1.0, v40
	v_add_f32_e32 v53, 1.0, v41
	v_rcp_f32_e32 v43, v42
	v_rcp_f32_e32 v42, v53
	v_add_f32_e32 v53, 1.0, v52
	v_rcp_f32_e32 v56, v53
	v_or_b32_e32 v53, 0x72, v116
	v_cmp_ge_u32_e64 s[0:1], v53, v91
	v_exp_f32_e64 v53, -|v63|
	v_mul_f32_e32 v57, v52, v56
	v_cmp_le_f32_e64 s[96:97], 0, v62
	s_and_b64 s[10:11], s[4:5], s[0:1]
	v_add_f32_e32 v58, 1.0, v53
	v_rcp_f32_e32 v59, v58
	v_or_b32_e32 v58, 0x73, v116
	v_cmp_ge_u32_e32 vcc, v58, v91
	v_cmp_le_f32_e64 s[0:1], 0, v63
	v_mul_f32_e32 v61, v53, v59
	v_mul_f32_e32 v54, v41, v42
	v_cndmask_b32_e64 v52, v56, v57, s[96:97]
	v_cndmask_b32_e64 v53, v59, v61, s[0:1]
	s_and_b64 s[12:13], s[4:5], vcc
	v_mul_f32_e32 v55, v40, v43
	v_cmp_le_f32_e64 s[92:93], 0, v60
	v_cndmask_b32_e64 v41, v42, v54, s[94:95]
	v_cndmask_b32_e64 v52, v52, 1.0, s[10:11]
	v_cndmask_b32_e64 v58, v53, 1.0, s[12:13]
	v_cndmask_b32_e64 v40, v43, v55, s[92:93]
	v_cndmask_b32_e64 v41, v41, 1.0, s[42:43]
	v_mul_f32_e32 v60, v58, v52
	v_cndmask_b32_e64 v40, v40, 1.0, s[8:9]
	v_mul_f32_e32 v62, v41, v60
	v_mul_f32_e32 v41, v40, v62
	ds_bpermute_b32 v53, v240, v41
	ds_bpermute_b32 v40, v241, v41
	s_waitcnt lgkmcnt(1)
	ds_bpermute_b32 v52, v241, v53
	s_and_saveexec_b64 s[14:15], s[70:71]
	s_xor_b64 vcc, exec, s[14:15]
	s_cbranch_execz .LBB0_306
	s_and_saveexec_b64 s[14:15], s[72:73]
	s_xor_b64 s[14:15], exec, s[14:15]
	v_cndmask_b32_e64 v63, 1.0, v53, s[74:75]
	s_andn2_saveexec_b64 s[14:15], s[14:15]
	s_cbranch_execz .LBB0_305
	s_waitcnt lgkmcnt(0)
	v_mul_f32_e32 v63, v40, v52

; __device__ __forceinline__ u32x2 pack4(f32x4 v) { return (u32x2){pk2(v[0], v[1]), pk2(v[2], v[3])}; }
; #define SB0 __builtin_amdgcn_sched_barrier(0)
; #define SK_LOAD(m_) do { kfr[(m_) & 1][0] = *(const LAS bf16x8*)(Ks + (16 * (m_) + fr) * 72 + 8 * fq); kfr[(m_) & 1][1] = *(const LAS bf16x8*)(Ks + (16 * (m_) + fr) * 72 + 32 + 8 * fq); } while (0)
; #define SB0 __builtin_amdgcn_sched_barrier(0)
; __device__ __forceinline__ void sb_unit(LAS unsigned char* lds, const bf16_t* P0, bf16_t* MIX, int b, int h, int qc) {
;     ...
;         for (int m = 7; m >= 0; --m) {
;             if (m > 0) SK_LOAD(m - 1);
;             SB0;
;             if (diag && m > w) { pk[m] = (u32x2){0u, 0u}; continue; }
;             f32x4 z = (f32x4){0.f, 0.f, 0.f, 0.f};
;             z = __builtin_amdgcn_mfma_f32_16x16x32_bf16(kfr[m & 1][0], qf0, z, 0, 0, 0);
;             z = __builtin_amdgcn_mfma_f32_16x16x32_bf16(kfr[m & 1][1], qf1, z, 0, 0, 0);
;             const int sb = kb * 128 + 16 * m + 4 * fq;
;             float be[4], om[4];
; #pragma unroll
;             for (int r = 0; r < 4; ++r) { const bool ok = !diag || (sb + r < tq);
;                 const float e = __builtin_amdgcn_exp2f(-fabsf(z[r])), inv = __builtin_amdgcn_rcpf(1.f + e), ei = e * inv;
;                 be[r] = ok ? (z[r] >= 0.f ? inv : ei) : 0.f; om[r] = ok ? (z[r] >= 0.f ? ei : inv) : 1.f; }
;             const float x3 = om[3], x2 = x3 * om[2], x1 = x2 * om[1], x0 = x1 * om[0];
;             const float t1 = __shfl_xor(x0, 16), t2 = __shfl_xor(x0, 32), t3 = __shfl_xor(t1, 32);
;             const float E = fq == 0 ? (t1 * t2 * t3) : fq == 1 ? (t2 * t3) : fq == 2 ? t1 : 1.f;
;             const float base = R * E;
;             f32x4 av;
;             av[0] = be[0] * (x1 * base); av[1] = be[1] * (x2 * base); av[2] = be[2] * (x3 * base); av[3] = be[3] * base;
;             pk[m] = pack4(av);
;             R *= (x0 * t1) * (t2 * t3);
.LBB0_309:
	s_or_b64 exec, exec, s[6:7]
	s_waitcnt lgkmcnt(3)
	ds_read_b128 v[56:59], v100 offset:11520
	s_waitcnt lgkmcnt(3)
	ds_read_b128 v[52:55], v100 offset:11584
	s_and_b64 s[0:1], s[80:81], s[4:5]
	v_mov_b32_e32 v41, 0
	s_xor_b64 s[0:1], s[0:1], -1
	v_mov_b32_e32 v40, v41
	s_and_saveexec_b64 s[6:7], s[0:1]
	s_cbranch_execz .LBB0_319
	s_waitcnt lgkmcnt(3)
	v_mfma_f32_16x16x32_bf16 v[48:51], v[48:51], v[0:3], 0
	v_or_b32_e32 v40, 0x60, v116
	v_cmp_ge_u32_e32 vcc, v40, v91
	v_or_b32_e32 v60, 0x62, v116
	s_waitcnt lgkmcnt(2)
	v_mfma_f32_16x16x32_bf16 v[44:47], v[44:47], v[4:7], v[48:51]
	s_and_b64 s[8:9], s[4:5], vcc
	v_cmp_ge_u32_e32 vcc, v60, v91
	v_or_b32_e32 v62, 0x63, v116
	v_or_b32_e32 v49, 0x61, v116
	v_cmp_ge_u32_e64 s[0:1], v49, v91
	s_nop 2
	v_exp_f32_e64 v48, -|v44|
	v_exp_f32_e64 v50, -|v45|
	v_exp_f32_e64 v60, -|v47|
	s_and_b64 s[42:43], s[4:5], s[0:1]
	v_add_f32_e32 v40, 1.0, v48
	v_add_f32_e32 v51, 1.0, v50
	v_rcp_f32_e32 v41, v40
	v_rcp_f32_e32 v40, v51
	v_exp_f32_e64 v51, -|v46|
	v_add_f32_e32 v61, 1.0, v60
	v_mul_f32_e32 v49, v48, v41
	v_mul_f32_e32 v48, v50, v40
	v_add_f32_e32 v50, 1.0, v51
	v_rcp_f32_e32 v50, v50
	v_rcp_f32_e32 v61, v61
	v_cmp_le_f32_e64 s[96:97], 0, v46
	s_and_b64 s[10:11], s[4:5], vcc
	v_mul_f32_e32 v51, v51, v50
	v_cmp_ge_u32_e32 vcc, v62, v91
	v_mul_f32_e32 v63, v60, v61
	v_cmp_le_f32_e64 s[0:1], 0, v47
	v_cmp_le_f32_e64 s[94:95], 0, v45
	v_cndmask_b32_e64 v46, v50, v51, s[96:97]
	v_cndmask_b32_e64 v47, v61, v63, s[0:1]
	s_and_b64 s[12:13], s[4:5], vcc
	v_cmp_le_f32_e64 s[92:93], 0, v44
	v_cndmask_b32_e64 v45, v40, v48, s[94:95]
	v_cndmask_b32_e64 v46, v46, 1.0, s[10:11]
	v_cndmask_b32_e64 v60, v47, 1.0, s[12:13]
	v_cndmask_b32_e64 v44, v41, v49, s[92:93]
	v_cndmask_b32_e64 v45, v45, 1.0, s[42:43]
	v_mul_f32_e32 v62, v60, v46
	v_cndmask_b32_e64 v44, v44, 1.0, s[8:9]
	v_mul_f32_e32 v64, v45, v62
	v_mul_f32_e32 v45, v44, v64
	ds_bpermute_b32 v47, v240, v45
	ds_bpermute_b32 v44, v241, v45
	s_waitcnt lgkmcnt(1)
	ds_bpermute_b32 v46, v241, v47
	s_and_saveexec_b64 s[14:15], s[70:71]
	s_xor_b64 vcc, exec, s[14:15]
	s_cbranch_execz .LBB0_316
	s_and_saveexec_b64 s[14:15], s[72:73]
	s_xor_b64 s[14:15], exec, s[14:15]
	v_cndmask_b32_e64 v65, 1.0, v47, s[74:75]
	s_andn2_saveexec_b64 s[14:15], s[14:15]
	s_cbranch_execz .LBB0_315
	s_waitcnt lgkmcnt(0)
	v_mul_f32_e32 v65, v44, v46

; __device__ __forceinline__ u32x2 pack4(f32x4 v) { return (u32x2){pk2(v[0], v[1]), pk2(v[2], v[3])}; }
; #define SB0 __builtin_amdgcn_sched_barrier(0)
; #define SK_LOAD(m_) do { kfr[(m_) & 1][0] = *(const LAS bf16x8*)(Ks + (16 * (m_) + fr) * 72 + 8 * fq); kfr[(m_) & 1][1] = *(const LAS bf16x8*)(Ks + (16 * (m_) + fr) * 72 + 32 + 8 * fq); } while (0)
; #define SB0 __builtin_amdgcn_sched_barrier(0)
; __device__ __forceinline__ void sb_unit(LAS unsigned char* lds, const bf16_t* P0, bf16_t* MIX, int b, int h, int qc) {
;     ...
;         for (int m = 7; m >= 0; --m) {
;             if (m > 0) SK_LOAD(m - 1);
;             SB0;
;             if (diag && m > w) { pk[m] = (u32x2){0u, 0u}; continue; }
;             f32x4 z = (f32x4){0.f, 0.f, 0.f, 0.f};
;             z = __builtin_amdgcn_mfma_f32_16x16x32_bf16(kfr[m & 1][0], qf0, z, 0, 0, 0);
;             z = __builtin_amdgcn_mfma_f32_16x16x32_bf16(kfr[m & 1][1], qf1, z, 0, 0, 0);
;             const int sb = kb * 128 + 16 * m + 4 * fq;
;             float be[4], om[4];
; #pragma unroll
;             for (int r = 0; r < 4; ++r) { const bool ok = !diag || (sb + r < tq);
;                 const float e = __builtin_amdgcn_exp2f(-fabsf(z[r])), inv = __builtin_amdgcn_rcpf(1.f + e), ei = e * inv;
;                 be[r] = ok ? (z[r] >= 0.f ? inv : ei) : 0.f; om[r] = ok ? (z[r] >= 0.f ? ei : inv) : 1.f; }
;             const float x3 = om[3], x2 = x3 * om[2], x1 = x2 * om[1], x0 = x1 * om[0];
;             const float t1 = __shfl_xor(x0, 16), t2 = __shfl_xor(x0, 32), t3 = __shfl_xor(t1, 32);
;             const float E = fq == 0 ? (t1 * t2 * t3) : fq == 1 ? (t2 * t3) : fq == 2 ? t1 : 1.f;
;             const float base = R * E;
;             f32x4 av;
;             av[0] = be[0] * (x1 * base); av[1] = be[1] * (x2 * base); av[2] = be[2] * (x3 * base); av[3] = be[3] * base;
;             pk[m] = pack4(av);
;             R *= (x0 * t1) * (t2 * t3);
.LBB0_319:
	s_or_b64 exec, exec, s[6:7]
	ds_read_b128 v[60:63], v100 offset:9216
	s_waitcnt lgkmcnt(4)
	ds_read_b128 v[48:51], v100 offset:9280
	s_and_b64 s[0:1], s[82:83], s[4:5]
	s_waitcnt lgkmcnt(4)
	v_mov_b32_e32 v47, 0
	s_xor_b64 s[0:1], s[0:1], -1
	v_mov_b32_e32 v46, v47
	s_and_saveexec_b64 s[6:7], s[0:1]
	s_cbranch_execz .LBB0_329
	s_waitcnt lgkmcnt(3)
	v_mfma_f32_16x16x32_bf16 v[44:47], v[56:59], v[0:3], 0
	v_or_b32_e32 v56, 0x50, v116
	v_cmp_ge_u32_e32 vcc, v56, v91
	s_and_b64 s[8:9], s[4:5], vcc
	s_waitcnt lgkmcnt(2)
	v_mfma_f32_16x16x32_bf16 v[64:67], v[52:55], v[4:7], v[44:47]
	v_or_b32_e32 v52, 0x51, v116
	v_cmp_ge_u32_e64 s[0:1], v52, v91
	s_and_b64 s[42:43], s[4:5], s[0:1]
	s_nop 4
	v_exp_f32_e64 v44, -|v64|
	v_exp_f32_e64 v45, -|v65|
	v_exp_f32_e64 v52, -|v66|
	v_cmp_le_f32_e64 s[94:95], 0, v65
	v_add_f32_e32 v46, 1.0, v44
	v_add_f32_e32 v53, 1.0, v45
	v_rcp_f32_e32 v47, v46
	v_rcp_f32_e32 v46, v53
	v_add_f32_e32 v53, 1.0, v52
	v_rcp_f32_e32 v56, v53
	v_or_b32_e32 v53, 0x52, v116
	v_cmp_ge_u32_e32 vcc, v53, v91
	v_exp_f32_e64 v53, -|v67|
	v_mul_f32_e32 v57, v52, v56
	v_cmp_le_f32_e64 s[96:97], 0, v66
	s_and_b64 s[10:11], s[4:5], vcc
	v_add_f32_e32 v58, 1.0, v53
	v_rcp_f32_e32 v59, v58
	v_or_b32_e32 v58, 0x53, v116
	v_cmp_ge_u32_e32 vcc, v58, v91
	v_cmp_le_f32_e64 s[0:1], 0, v67
	v_mul_f32_e32 v65, v53, v59
	v_mul_f32_e32 v54, v45, v46
	v_cndmask_b32_e64 v52, v56, v57, s[96:97]
	v_cndmask_b32_e64 v53, v59, v65, s[0:1]
	s_and_b64 s[12:13], s[4:5], vcc
	v_mul_f32_e32 v55, v44, v47
	v_cmp_le_f32_e64 s[92:93], 0, v64
	v_cndmask_b32_e64 v45, v46, v54, s[94:95]
	v_cndmask_b32_e64 v52, v52, 1.0, s[10:11]
	v_cndmask_b32_e64 v58, v53, 1.0, s[12:13]
	v_cndmask_b32_e64 v44, v47, v55, s[92:93]
	v_cndmask_b32_e64 v45, v45, 1.0, s[42:43]
	v_mul_f32_e32 v64, v58, v52
	v_cndmask_b32_e64 v44, v44, 1.0, s[8:9]
	v_mul_f32_e32 v66, v45, v64
	v_mul_f32_e32 v45, v44, v66
	ds_bpermute_b32 v53, v240, v45
	ds_bpermute_b32 v44, v241, v45
	s_waitcnt lgkmcnt(1)
	ds_bpermute_b32 v52, v241, v53
	s_and_saveexec_b64 s[14:15], s[70:71]
	s_xor_b64 vcc, exec, s[14:15]
	s_cbranch_execz .LBB0_326
	s_and_saveexec_b64 s[14:15], s[72:73]
	s_xor_b64 s[14:15], exec, s[14:15]
	v_cndmask_b32_e64 v67, 1.0, v53, s[74:75]
	s_andn2_saveexec_b64 s[14:15], s[14:15]
	s_cbranch_execz .LBB0_325
	s_waitcnt lgkmcnt(0)
	v_mul_f32_e32 v67, v44, v52

; __device__ __forceinline__ u32x2 pack4(f32x4 v) { return (u32x2){pk2(v[0], v[1]), pk2(v[2], v[3])}; }
; #define SB0 __builtin_amdgcn_sched_barrier(0)
; #define SK_LOAD(m_) do { kfr[(m_) & 1][0] = *(const LAS bf16x8*)(Ks + (16 * (m_) + fr) * 72 + 8 * fq); kfr[(m_) & 1][1] = *(const LAS bf16x8*)(Ks + (16 * (m_) + fr) * 72 + 32 + 8 * fq); } while (0)
; #define SB0 __builtin_amdgcn_sched_barrier(0)
; __device__ __forceinline__ void sb_unit(LAS unsigned char* lds, const bf16_t* P0, bf16_t* MIX, int b, int h, int qc) {
;     ...
;         for (int m = 7; m >= 0; --m) {
;             if (m > 0) SK_LOAD(m - 1);
;             SB0;
;             if (diag && m > w) { pk[m] = (u32x2){0u, 0u}; continue; }
;             f32x4 z = (f32x4){0.f, 0.f, 0.f, 0.f};
;             z = __builtin_amdgcn_mfma_f32_16x16x32_bf16(kfr[m & 1][0], qf0, z, 0, 0, 0);
;             z = __builtin_amdgcn_mfma_f32_16x16x32_bf16(kfr[m & 1][1], qf1, z, 0, 0, 0);
;             const int sb = kb * 128 + 16 * m + 4 * fq;
;             float be[4], om[4];
; #pragma unroll
;             for (int r = 0; r < 4; ++r) { const bool ok = !diag || (sb + r < tq);
;                 const float e = __builtin_amdgcn_exp2f(-fabsf(z[r])), inv = __builtin_amdgcn_rcpf(1.f + e), ei = e * inv;
;                 be[r] = ok ? (z[r] >= 0.f ? inv : ei) : 0.f; om[r] = ok ? (z[r] >= 0.f ? ei : inv) : 1.f; }
;             const float x3 = om[3], x2 = x3 * om[2], x1 = x2 * om[1], x0 = x1 * om[0];
;             const float t1 = __shfl_xor(x0, 16), t2 = __shfl_xor(x0, 32), t3 = __shfl_xor(t1, 32);
;             const float E = fq == 0 ? (t1 * t2 * t3) : fq == 1 ? (t2 * t3) : fq == 2 ? t1 : 1.f;
;             const float base = R * E;
;             f32x4 av;
;             av[0] = be[0] * (x1 * base); av[1] = be[1] * (x2 * base); av[2] = be[2] * (x3 * base); av[3] = be[3] * base;
;             pk[m] = pack4(av);
;             R *= (x0 * t1) * (t2 * t3);
.LBB0_329:
	s_or_b64 exec, exec, s[6:7]
	ds_read_b128 v[64:67], v100 offset:6912
	s_waitcnt lgkmcnt(3)
	ds_read_b128 v[52:55], v100 offset:6976
	s_and_b64 s[0:1], s[84:85], s[4:5]
	v_mov_b32_e32 v45, 0
	s_xor_b64 s[0:1], s[0:1], -1
	v_mov_b32_e32 v44, v45
	s_and_saveexec_b64 s[6:7], s[0:1]
	s_cbranch_execz .LBB0_339
	s_waitcnt lgkmcnt(3)
	v_mfma_f32_16x16x32_bf16 v[56:59], v[60:63], v[0:3], 0
	v_or_b32_e32 v44, 64, v116
	v_cmp_ge_u32_e32 vcc, v44, v91
	v_or_b32_e32 v60, 0x42, v116
	s_waitcnt lgkmcnt(2)
	v_mfma_f32_16x16x32_bf16 v[48:51], v[48:51], v[4:7], v[56:59]
	s_and_b64 s[8:9], s[4:5], vcc
	v_cmp_ge_u32_e32 vcc, v60, v91
	v_or_b32_e32 v62, 0x43, v116
	v_or_b32_e32 v57, 0x41, v116
	v_cmp_ge_u32_e64 s[0:1], v57, v91
	s_nop 2
	v_exp_f32_e64 v56, -|v48|
	v_exp_f32_e64 v58, -|v49|
	v_exp_f32_e64 v60, -|v51|
	s_and_b64 s[42:43], s[4:5], s[0:1]
	v_add_f32_e32 v44, 1.0, v56
	v_add_f32_e32 v59, 1.0, v58
	v_rcp_f32_e32 v45, v44
	v_rcp_f32_e32 v44, v59
	v_exp_f32_e64 v59, -|v50|
	v_add_f32_e32 v61, 1.0, v60
	v_mul_f32_e32 v57, v56, v45
	v_mul_f32_e32 v56, v58, v44
	v_add_f32_e32 v58, 1.0, v59
	v_rcp_f32_e32 v58, v58
	v_rcp_f32_e32 v61, v61
	v_cmp_le_f32_e64 s[96:97], 0, v50
	s_and_b64 s[10:11], s[4:5], vcc
	v_mul_f32_e32 v59, v59, v58
	v_cmp_ge_u32_e32 vcc, v62, v91
	v_mul_f32_e32 v63, v60, v61
	v_cmp_le_f32_e64 s[0:1], 0, v51
	v_cmp_le_f32_e64 s[94:95], 0, v49
	v_cndmask_b32_e64 v50, v58, v59, s[96:97]
	v_cndmask_b32_e64 v51, v61, v63, s[0:1]
	s_and_b64 s[12:13], s[4:5], vcc
	v_cmp_le_f32_e64 s[92:93], 0, v48
	v_cndmask_b32_e64 v49, v44, v56, s[94:95]
	v_cndmask_b32_e64 v50, v50, 1.0, s[10:11]
	v_cndmask_b32_e64 v60, v51, 1.0, s[12:13]
	v_cndmask_b32_e64 v48, v45, v57, s[92:93]
	v_cndmask_b32_e64 v49, v49, 1.0, s[42:43]
	v_mul_f32_e32 v62, v60, v50
	v_cndmask_b32_e64 v48, v48, 1.0, s[8:9]
	v_mul_f32_e32 v68, v49, v62
	v_mul_f32_e32 v49, v48, v68
	ds_bpermute_b32 v51, v240, v49
	ds_bpermute_b32 v48, v241, v49
	s_waitcnt lgkmcnt(1)
	ds_bpermute_b32 v50, v241, v51
	s_and_saveexec_b64 s[14:15], s[70:71]
	s_xor_b64 vcc, exec, s[14:15]
	s_cbranch_execz .LBB0_336
	s_and_saveexec_b64 s[14:15], s[72:73]
	s_xor_b64 s[14:15], exec, s[14:15]
	v_cndmask_b32_e64 v69, 1.0, v51, s[74:75]
	s_andn2_saveexec_b64 s[14:15], s[14:15]
	s_cbranch_execz .LBB0_335
	s_waitcnt lgkmcnt(0)
	v_mul_f32_e32 v69, v48, v50

; __device__ __forceinline__ u32x2 pack4(f32x4 v) { return (u32x2){pk2(v[0], v[1]), pk2(v[2], v[3])}; }
; #define SB0 __builtin_amdgcn_sched_barrier(0)
; #define SK_LOAD(m_) do { kfr[(m_) & 1][0] = *(const LAS bf16x8*)(Ks + (16 * (m_) + fr) * 72 + 8 * fq); kfr[(m_) & 1][1] = *(const LAS bf16x8*)(Ks + (16 * (m_) + fr) * 72 + 32 + 8 * fq); } while (0)
; #define SB0 __builtin_amdgcn_sched_barrier(0)
; __device__ __forceinline__ void sb_unit(LAS unsigned char* lds, const bf16_t* P0, bf16_t* MIX, int b, int h, int qc) {
;     ...
;         for (int m = 7; m >= 0; --m) {
;             if (m > 0) SK_LOAD(m - 1);
;             SB0;
;             if (diag && m > w) { pk[m] = (u32x2){0u, 0u}; continue; }
;             f32x4 z = (f32x4){0.f, 0.f, 0.f, 0.f};
;             z = __builtin_amdgcn_mfma_f32_16x16x32_bf16(kfr[m & 1][0], qf0, z, 0, 0, 0);
;             z = __builtin_amdgcn_mfma_f32_16x16x32_bf16(kfr[m & 1][1], qf1, z, 0, 0, 0);
;             const int sb = kb * 128 + 16 * m + 4 * fq;
;             float be[4], om[4];
; #pragma unroll
;             for (int r = 0; r < 4; ++r) { const bool ok = !diag || (sb + r < tq);
;                 const float e = __builtin_amdgcn_exp2f(-fabsf(z[r])), inv = __builtin_amdgcn_rcpf(1.f + e), ei = e * inv;
;                 be[r] = ok ? (z[r] >= 0.f ? inv : ei) : 0.f; om[r] = ok ? (z[r] >= 0.f ? ei : inv) : 1.f; }
;             const float x3 = om[3], x2 = x3 * om[2], x1 = x2 * om[1], x0 = x1 * om[0];
;             const float t1 = __shfl_xor(x0, 16), t2 = __shfl_xor(x0, 32), t3 = __shfl_xor(t1, 32);
;             const float E = fq == 0 ? (t1 * t2 * t3) : fq == 1 ? (t2 * t3) : fq == 2 ? t1 : 1.f;
;             const float base = R * E;
;             f32x4 av;
;             av[0] = be[0] * (x1 * base); av[1] = be[1] * (x2 * base); av[2] = be[2] * (x3 * base); av[3] = be[3] * base;
;             pk[m] = pack4(av);
;             R *= (x0 * t1) * (t2 * t3);
.LBB0_339:
	s_or_b64 exec, exec, s[6:7]
	s_waitcnt lgkmcnt(3)
	ds_read_b128 v[60:63], v100 offset:4608
	ds_read_b128 v[56:59], v100 offset:4672
	s_and_b64 s[0:1], s[86:87], s[4:5]
	s_waitcnt lgkmcnt(4)
	v_mov_b32_e32 v51, 0
	s_xor_b64 s[0:1], s[0:1], -1
	v_mov_b32_e32 v50, v51
	s_and_saveexec_b64 s[6:7], s[0:1]
	s_cbranch_execz .LBB0_349
	s_waitcnt lgkmcnt(3)
	v_mfma_f32_16x16x32_bf16 v[48:51], v[64:67], v[0:3], 0
	v_or_b32_e32 v64, 48, v116
	v_cmp_ge_u32_e32 vcc, v64, v91
	s_and_b64 s[8:9], s[4:5], vcc
	s_waitcnt lgkmcnt(2)
	v_mfma_f32_16x16x32_bf16 v[68:71], v[52:55], v[4:7], v[48:51]
	v_or_b32_e32 v52, 49, v116
	v_cmp_ge_u32_e64 s[0:1], v52, v91
	s_and_b64 s[42:43], s[4:5], s[0:1]
	s_nop 4
	v_exp_f32_e64 v48, -|v68|
	v_exp_f32_e64 v49, -|v69|
	v_exp_f32_e64 v52, -|v70|
	v_cmp_le_f32_e64 s[94:95], 0, v69
	v_add_f32_e32 v50, 1.0, v48
	v_add_f32_e32 v53, 1.0, v49
	v_rcp_f32_e32 v51, v50
	v_rcp_f32_e32 v50, v53
	v_add_f32_e32 v53, 1.0, v52
	v_rcp_f32_e32 v64, v53
	v_or_b32_e32 v53, 50, v116
	v_cmp_ge_u32_e32 vcc, v53, v91
	v_exp_f32_e64 v53, -|v71|
	v_mul_f32_e32 v65, v52, v64
	v_cmp_le_f32_e64 s[96:97], 0, v70
	s_and_b64 s[10:11], s[4:5], vcc
	v_add_f32_e32 v66, 1.0, v53
	v_rcp_f32_e32 v67, v66
	v_or_b32_e32 v66, 51, v116
	v_cmp_ge_u32_e32 vcc, v66, v91
	v_cmp_le_f32_e64 s[0:1], 0, v71
	v_mul_f32_e32 v69, v53, v67
	v_mul_f32_e32 v54, v49, v50
	v_cndmask_b32_e64 v52, v64, v65, s[96:97]
	v_cndmask_b32_e64 v53, v67, v69, s[0:1]
	s_and_b64 s[12:13], s[4:5], vcc
	v_mul_f32_e32 v55, v48, v51
	v_cmp_le_f32_e64 s[92:93], 0, v68
	v_cndmask_b32_e64 v49, v50, v54, s[94:95]
	v_cndmask_b32_e64 v52, v52, 1.0, s[10:11]
	v_cndmask_b32_e64 v66, v53, 1.0, s[12:13]
	v_cndmask_b32_e64 v48, v51, v55, s[92:93]
	v_cndmask_b32_e64 v49, v49, 1.0, s[42:43]
	v_mul_f32_e32 v68, v66, v52
	v_cndmask_b32_e64 v48, v48, 1.0, s[8:9]
	v_mul_f32_e32 v70, v49, v68
	v_mul_f32_e32 v49, v48, v70
	ds_bpermute_b32 v53, v240, v49
	ds_bpermute_b32 v48, v241, v49
	s_waitcnt lgkmcnt(1)
	ds_bpermute_b32 v52, v241, v53
	s_and_saveexec_b64 s[14:15], s[70:71]
	s_xor_b64 vcc, exec, s[14:15]
	s_cbranch_execz .LBB0_346
	s_and_saveexec_b64 s[14:15], s[72:73]
	s_xor_b64 s[14:15], exec, s[14:15]
	v_cndmask_b32_e64 v71, 1.0, v53, s[74:75]
	s_andn2_saveexec_b64 s[14:15], s[14:15]
	s_cbranch_execz .LBB0_345
	s_waitcnt lgkmcnt(0)
	v_mul_f32_e32 v71, v48, v52

; __device__ __forceinline__ u32x2 pack4(f32x4 v) { return (u32x2){pk2(v[0], v[1]), pk2(v[2], v[3])}; }
; #define SB0 __builtin_amdgcn_sched_barrier(0)
; #define SK_LOAD(m_) do { kfr[(m_) & 1][0] = *(const LAS bf16x8*)(Ks + (16 * (m_) + fr) * 72 + 8 * fq); kfr[(m_) & 1][1] = *(const LAS bf16x8*)(Ks + (16 * (m_) + fr) * 72 + 32 + 8 * fq); } while (0)
; #define SB0 __builtin_amdgcn_sched_barrier(0)
; __device__ __forceinline__ void sb_unit(LAS unsigned char* lds, const bf16_t* P0, bf16_t* MIX, int b, int h, int qc) {
;     ...
;         for (int m = 7; m >= 0; --m) {
;             if (m > 0) SK_LOAD(m - 1);
;             SB0;
;             if (diag && m > w) { pk[m] = (u32x2){0u, 0u}; continue; }
;             f32x4 z = (f32x4){0.f, 0.f, 0.f, 0.f};
;             z = __builtin_amdgcn_mfma_f32_16x16x32_bf16(kfr[m & 1][0], qf0, z, 0, 0, 0);
;             z = __builtin_amdgcn_mfma_f32_16x16x32_bf16(kfr[m & 1][1], qf1, z, 0, 0, 0);
;             const int sb = kb * 128 + 16 * m + 4 * fq;
;             float be[4], om[4];
; #pragma unroll
;             for (int r = 0; r < 4; ++r) { const bool ok = !diag || (sb + r < tq);
;                 const float e = __builtin_amdgcn_exp2f(-fabsf(z[r])), inv = __builtin_amdgcn_rcpf(1.f + e), ei = e * inv;
;                 be[r] = ok ? (z[r] >= 0.f ? inv : ei) : 0.f; om[r] = ok ? (z[r] >= 0.f ? ei : inv) : 1.f; }
;             const float x3 = om[3], x2 = x3 * om[2], x1 = x2 * om[1], x0 = x1 * om[0];
;             const float t1 = __shfl_xor(x0, 16), t2 = __shfl_xor(x0, 32), t3 = __shfl_xor(t1, 32);
;             const float E = fq == 0 ? (t1 * t2 * t3) : fq == 1 ? (t2 * t3) : fq == 2 ? t1 : 1.f;
;             const float base = R * E;
;             f32x4 av;
;             av[0] = be[0] * (x1 * base); av[1] = be[1] * (x2 * base); av[2] = be[2] * (x3 * base); av[3] = be[3] * base;
;             pk[m] = pack4(av);
;             R *= (x0 * t1) * (t2 * t3);
.LBB0_349:
	s_or_b64 exec, exec, s[6:7]
	ds_read_b128 v[68:71], v100 offset:2304
	s_waitcnt lgkmcnt(4)
	ds_read_b128 v[64:67], v100 offset:2368
	s_and_b64 s[0:1], s[88:89], s[4:5]
	v_mov_b32_e32 v49, 0
	s_xor_b64 s[0:1], s[0:1], -1
	v_mov_b32_e32 v48, v49
	s_and_saveexec_b64 s[6:7], s[0:1]
	s_cbranch_execz .LBB0_359
	s_waitcnt lgkmcnt(3)
	v_mfma_f32_16x16x32_bf16 v[52:55], v[60:63], v[0:3], 0
	v_or_b32_e32 v48, 32, v116
	v_cmp_ge_u32_e32 vcc, v48, v91
	v_or_b32_e32 v60, 34, v116
	s_waitcnt lgkmcnt(2)
	v_mfma_f32_16x16x32_bf16 v[52:55], v[56:59], v[4:7], v[52:55]
	s_and_b64 s[8:9], s[4:5], vcc
	v_cmp_ge_u32_e32 vcc, v60, v91
	v_or_b32_e32 v57, 33, v116
	v_cmp_ge_u32_e64 s[0:1], v57, v91
	v_or_b32_e32 v62, 35, v116
	s_nop 2
	v_exp_f32_e64 v56, -|v52|
	v_exp_f32_e64 v58, -|v53|
	v_exp_f32_e64 v60, -|v55|
	s_and_b64 s[42:43], s[4:5], s[0:1]
	v_add_f32_e32 v48, 1.0, v56
	v_add_f32_e32 v59, 1.0, v58
	v_rcp_f32_e32 v49, v48
	v_rcp_f32_e32 v48, v59
	v_exp_f32_e64 v59, -|v54|
	v_add_f32_e32 v61, 1.0, v60
	v_mul_f32_e32 v57, v56, v49
	v_mul_f32_e32 v56, v58, v48
	v_add_f32_e32 v58, 1.0, v59
	v_rcp_f32_e32 v58, v58
	v_rcp_f32_e32 v61, v61
	v_cmp_le_f32_e64 s[96:97], 0, v54
	s_and_b64 s[10:11], s[4:5], vcc
	v_mul_f32_e32 v59, v59, v58
	v_cmp_ge_u32_e32 vcc, v62, v91
	v_mul_f32_e32 v63, v60, v61
	v_cmp_le_f32_e64 s[0:1], 0, v55
	v_cmp_le_f32_e64 s[94:95], 0, v53
	v_cndmask_b32_e64 v54, v58, v59, s[96:97]
	v_cndmask_b32_e64 v55, v61, v63, s[0:1]
	s_and_b64 s[12:13], s[4:5], vcc
	v_cmp_le_f32_e64 s[92:93], 0, v52
	v_cndmask_b32_e64 v53, v48, v56, s[94:95]
	v_cndmask_b32_e64 v54, v54, 1.0, s[10:11]
	v_cndmask_b32_e64 v60, v55, 1.0, s[12:13]
	v_cndmask_b32_e64 v52, v49, v57, s[92:93]
	v_cndmask_b32_e64 v53, v53, 1.0, s[42:43]
	v_mul_f32_e32 v62, v60, v54
	v_cndmask_b32_e64 v52, v52, 1.0, s[8:9]
	v_mul_f32_e32 v117, v53, v62
	v_mul_f32_e32 v53, v52, v117
	ds_bpermute_b32 v55, v240, v53
	ds_bpermute_b32 v52, v241, v53
	s_waitcnt lgkmcnt(1)
	ds_bpermute_b32 v54, v241, v55
	s_and_saveexec_b64 s[14:15], s[70:71]
	s_xor_b64 vcc, exec, s[14:15]
	s_cbranch_execz .LBB0_356
	s_and_saveexec_b64 s[14:15], s[72:73]
	s_xor_b64 s[14:15], exec, s[14:15]
	v_cndmask_b32_e64 v118, 1.0, v55, s[74:75]
	s_andn2_saveexec_b64 s[14:15], s[14:15]
	s_cbranch_execz .LBB0_355
	s_waitcnt lgkmcnt(0)
	v_mul_f32_e32 v118, v52, v54
